# first adaLN item's first six weight loads issued behind the silu(c) staging loads (before the staging arithmetic)
# baseline (speedup 1.0000x reference)
.LBB0_19:
	v_mov_b32_e32 v0, v252
	s_movk_i32 s0, 0x2000
	s_nop 0
	v_cmp_gt_i32_e32 vcc, s0, v0
	s_and_saveexec_b64 s[4:5], vcc
	s_cbranch_execz .LBB0_22
	v_lshlrev_b32_e32 v140, 2, v252
	s_mov_b32 s6, s18
	s_mov_b32 s7, s19
	global_load_dword v124, v140, s[6:7]
	global_load_dword v125, v140, s[6:7] offset:2048
	s_add_u32 s6, s6, 0x1000
	s_addc_u32 s7, s7, 0
	global_load_dword v126, v140, s[6:7]
	global_load_dword v127, v140, s[6:7] offset:2048
	s_add_u32 s6, s6, 0x1000
	s_addc_u32 s7, s7, 0
	global_load_dword v128, v140, s[6:7]
	global_load_dword v129, v140, s[6:7] offset:2048
	s_add_u32 s6, s6, 0x1000
	s_addc_u32 s7, s7, 0
	global_load_dword v130, v140, s[6:7]
	global_load_dword v131, v140, s[6:7] offset:2048
	s_add_u32 s6, s6, 0x1000
	s_addc_u32 s7, s7, 0
	global_load_dword v132, v140, s[6:7]
	global_load_dword v133, v140, s[6:7] offset:2048
	s_add_u32 s6, s6, 0x1000
	s_addc_u32 s7, s7, 0
	global_load_dword v134, v140, s[6:7]
	global_load_dword v135, v140, s[6:7] offset:2048
	s_add_u32 s6, s6, 0x1000
	s_addc_u32 s7, s7, 0
	global_load_dword v136, v140, s[6:7]
	global_load_dword v137, v140, s[6:7] offset:2048
	s_add_u32 s6, s6, 0x1000
	s_addc_u32 s7, s7, 0
	global_load_dword v138, v140, s[6:7]
	global_load_dword v139, v140, s[6:7] offset:2048
	s_cmpk_gt_i32 s2, 0x2ff
	s_cbranch_scc1 .Lada_pre_none
	v_lshlrev_b32_e32 v8, 2, v252
	v_and_b32_e32 v8, 60, v8
	v_and_b32_e32 v9, -16, v252
	s_mov_b32 s3, 0xc000
	s_mul_hi_i32 s0, s2, 0x2aaaaaab
	s_lshr_b32 s1, s0, 31
	s_ashr_i32 s99, s0, 5
	s_add_i32 s99, s99, s1
	s_mul_i32 s0, s99, 0xc0
	s_sub_i32 s0, s2, s0
	s_lshl_b32 s98, s0, 6
	v_or_b32_e32 v148, s98, v8
	v_ashrrev_i32_e32 v149, 31, v148
	v_lshl_add_u32 v13, s99, 9, v9
	v_lshl_add_u64 v[6:7], v[148:149], 2, s[22:23]
	v_mad_i64_i32 v[148:149], s[0:1], v13, s3, v[6:7]
	global_load_dwordx4 v[14:17], v[148:149], off nt
	v_or_b32_e32 v148, 1, v13
	v_mad_i64_i32 v[148:149], s[0:1], v148, s3, v[6:7]
	global_load_dwordx4 v[18:21], v[148:149], off nt
	v_or_b32_e32 v148, 2, v13
	v_mad_i64_i32 v[148:149], s[0:1], v148, s3, v[6:7]
	global_load_dwordx4 v[22:25], v[148:149], off nt
	v_or_b32_e32 v148, 3, v13
	v_mad_i64_i32 v[148:149], s[0:1], v148, s3, v[6:7]
	global_load_dwordx4 v[26:29], v[148:149], off nt
	v_or_b32_e32 v148, 4, v13
	v_mad_i64_i32 v[148:149], s[0:1], v148, s3, v[6:7]
	global_load_dwordx4 v[30:33], v[148:149], off nt
	v_or_b32_e32 v148, 5, v13
	v_mad_i64_i32 v[148:149], s[0:1], v148, s3, v[6:7]
	global_load_dwordx4 v[34:37], v[148:149], off nt
	s_branch .Lada_pre_done
.Lada_pre_none:
	global_load_dwordx4 v[14:17], v140, s[18:19]
	global_load_dwordx4 v[18:21], v140, s[18:19]
	global_load_dwordx4 v[22:25], v140, s[18:19]
	global_load_dwordx4 v[26:29], v140, s[18:19]
	global_load_dwordx4 v[30:33], v140, s[18:19]
	global_load_dwordx4 v[34:37], v140, s[18:19]
.Lada_pre_done:
	s_waitcnt vmcnt(21)
	v_mul_f32_e32 v141, 0xbfb8aa3b, v124
	v_exp_f32_e32 v141, v141
	s_nop 0
	v_add_f32_e32 v141, 1.0, v141
	v_div_scale_f32 v142, s[10:11], v141, v141, v124
	v_rcp_f32_e32 v143, v142
	v_div_scale_f32 v144, vcc, v124, v141, v124
	v_fma_f32 v145, -v142, v143, 1.0
	v_fmac_f32_e32 v143, v145, v143
	v_mul_f32_e32 v145, v144, v143
	v_fma_f32 v146, -v142, v145, v144
	v_fmac_f32_e32 v145, v146, v143
	v_fma_f32 v142, -v142, v145, v144
	v_div_fmas_f32 v142, v142, v143, v145
	v_div_fixup_f32 v147, v142, v141, v124
	ds_write_b32 v140, v147 offset:0
	s_waitcnt vmcnt(20)
	v_mul_f32_e32 v141, 0xbfb8aa3b, v125
	v_exp_f32_e32 v141, v141
	s_nop 0
	v_add_f32_e32 v141, 1.0, v141
	v_div_scale_f32 v142, s[10:11], v141, v141, v125
	v_rcp_f32_e32 v143, v142
	v_div_scale_f32 v144, vcc, v125, v141, v125
	v_fma_f32 v145, -v142, v143, 1.0
	v_fmac_f32_e32 v143, v145, v143
	v_mul_f32_e32 v145, v144, v143
	v_fma_f32 v146, -v142, v145, v144
	v_fmac_f32_e32 v145, v146, v143
	v_fma_f32 v142, -v142, v145, v144
	v_div_fmas_f32 v142, v142, v143, v145
	v_div_fixup_f32 v147, v142, v141, v125
	ds_write_b32 v140, v147 offset:2048
	s_waitcnt vmcnt(19)
	v_mul_f32_e32 v141, 0xbfb8aa3b, v126
	v_exp_f32_e32 v141, v141
	s_nop 0
	v_add_f32_e32 v141, 1.0, v141
	v_div_scale_f32 v142, s[10:11], v141, v141, v126
	v_rcp_f32_e32 v143, v142
	v_div_scale_f32 v144, vcc, v126, v141, v126
	v_fma_f32 v145, -v142, v143, 1.0
	v_fmac_f32_e32 v143, v145, v143
	v_mul_f32_e32 v145, v144, v143
	v_fma_f32 v146, -v142, v145, v144
	v_fmac_f32_e32 v145, v146, v143
	v_fma_f32 v142, -v142, v145, v144
	v_div_fmas_f32 v142, v142, v143, v145
	v_div_fixup_f32 v147, v142, v141, v126
	ds_write_b32 v140, v147 offset:4096
	s_waitcnt vmcnt(18)
	v_mul_f32_e32 v141, 0xbfb8aa3b, v127
	v_exp_f32_e32 v141, v141
	s_nop 0
	v_add_f32_e32 v141, 1.0, v141
	v_div_scale_f32 v142, s[10:11], v141, v141, v127
	v_rcp_f32_e32 v143, v142
	v_div_scale_f32 v144, vcc, v127, v141, v127
	v_fma_f32 v145, -v142, v143, 1.0
	v_fmac_f32_e32 v143, v145, v143
	v_mul_f32_e32 v145, v144, v143
	v_fma_f32 v146, -v142, v145, v144
	v_fmac_f32_e32 v145, v146, v143
	v_fma_f32 v142, -v142, v145, v144
	v_div_fmas_f32 v142, v142, v143, v145
	v_div_fixup_f32 v147, v142, v141, v127
	ds_write_b32 v140, v147 offset:6144
	s_waitcnt vmcnt(17)
	v_mul_f32_e32 v141, 0xbfb8aa3b, v128
	v_exp_f32_e32 v141, v141
	s_nop 0
	v_add_f32_e32 v141, 1.0, v141
	v_div_scale_f32 v142, s[10:11], v141, v141, v128
	v_rcp_f32_e32 v143, v142
	v_div_scale_f32 v144, vcc, v128, v141, v128
	v_fma_f32 v145, -v142, v143, 1.0
	v_fmac_f32_e32 v143, v145, v143
	v_mul_f32_e32 v145, v144, v143
	v_fma_f32 v146, -v142, v145, v144
	v_fmac_f32_e32 v145, v146, v143
	v_fma_f32 v142, -v142, v145, v144
	v_div_fmas_f32 v142, v142, v143, v145
	v_div_fixup_f32 v147, v142, v141, v128
	ds_write_b32 v140, v147 offset:8192
	s_waitcnt vmcnt(16)
	v_mul_f32_e32 v141, 0xbfb8aa3b, v129
	v_exp_f32_e32 v141, v141
	s_nop 0
	v_add_f32_e32 v141, 1.0, v141
	v_div_scale_f32 v142, s[10:11], v141, v141, v129
	v_rcp_f32_e32 v143, v142
	v_div_scale_f32 v144, vcc, v129, v141, v129
	v_fma_f32 v145, -v142, v143, 1.0
	v_fmac_f32_e32 v143, v145, v143
	v_mul_f32_e32 v145, v144, v143
	v_fma_f32 v146, -v142, v145, v144
	v_fmac_f32_e32 v145, v146, v143
	v_fma_f32 v142, -v142, v145, v144
	v_div_fmas_f32 v142, v142, v143, v145
	v_div_fixup_f32 v147, v142, v141, v129
	ds_write_b32 v140, v147 offset:10240
	s_waitcnt vmcnt(15)
	v_mul_f32_e32 v141, 0xbfb8aa3b, v130
	v_exp_f32_e32 v141, v141
	s_nop 0
	v_add_f32_e32 v141, 1.0, v141
	v_div_scale_f32 v142, s[10:11], v141, v141, v130
	v_rcp_f32_e32 v143, v142
	v_div_scale_f32 v144, vcc, v130, v141, v130
	v_fma_f32 v145, -v142, v143, 1.0
	v_fmac_f32_e32 v143, v145, v143
	v_mul_f32_e32 v145, v144, v143
	v_fma_f32 v146, -v142, v145, v144
	v_fmac_f32_e32 v145, v146, v143
	v_fma_f32 v142, -v142, v145, v144
	v_div_fmas_f32 v142, v142, v143, v145
	v_div_fixup_f32 v147, v142, v141, v130
	ds_write_b32 v140, v147 offset:12288
	s_waitcnt vmcnt(14)
	v_mul_f32_e32 v141, 0xbfb8aa3b, v131
	v_exp_f32_e32 v141, v141
	s_nop 0
	v_add_f32_e32 v141, 1.0, v141
	v_div_scale_f32 v142, s[10:11], v141, v141, v131
	v_rcp_f32_e32 v143, v142
	v_div_scale_f32 v144, vcc, v131, v141, v131
	v_fma_f32 v145, -v142, v143, 1.0
	v_fmac_f32_e32 v143, v145, v143
	v_mul_f32_e32 v145, v144, v143
	v_fma_f32 v146, -v142, v145, v144
	v_fmac_f32_e32 v145, v146, v143
	v_fma_f32 v142, -v142, v145, v144
	v_div_fmas_f32 v142, v142, v143, v145
	v_div_fixup_f32 v147, v142, v141, v131
	ds_write_b32 v140, v147 offset:14336
	s_waitcnt vmcnt(13)
	v_mul_f32_e32 v141, 0xbfb8aa3b, v132
	v_exp_f32_e32 v141, v141
	s_nop 0
	v_add_f32_e32 v141, 1.0, v141
	v_div_scale_f32 v142, s[10:11], v141, v141, v132
	v_rcp_f32_e32 v143, v142
	v_div_scale_f32 v144, vcc, v132, v141, v132
	v_fma_f32 v145, -v142, v143, 1.0
	v_fmac_f32_e32 v143, v145, v143
	v_mul_f32_e32 v145, v144, v143
	v_fma_f32 v146, -v142, v145, v144
	v_fmac_f32_e32 v145, v146, v143
	v_fma_f32 v142, -v142, v145, v144
	v_div_fmas_f32 v142, v142, v143, v145
	v_div_fixup_f32 v147, v142, v141, v132
	ds_write_b32 v140, v147 offset:16384
	s_waitcnt vmcnt(12)
	v_mul_f32_e32 v141, 0xbfb8aa3b, v133
	v_exp_f32_e32 v141, v141
	s_nop 0
	v_add_f32_e32 v141, 1.0, v141
	v_div_scale_f32 v142, s[10:11], v141, v141, v133
	v_rcp_f32_e32 v143, v142
	v_div_scale_f32 v144, vcc, v133, v141, v133
	v_fma_f32 v145, -v142, v143, 1.0
	v_fmac_f32_e32 v143, v145, v143
	v_mul_f32_e32 v145, v144, v143
	v_fma_f32 v146, -v142, v145, v144
	v_fmac_f32_e32 v145, v146, v143
	v_fma_f32 v142, -v142, v145, v144
	v_div_fmas_f32 v142, v142, v143, v145
	v_div_fixup_f32 v147, v142, v141, v133
	ds_write_b32 v140, v147 offset:18432
	s_waitcnt vmcnt(11)
	v_mul_f32_e32 v141, 0xbfb8aa3b, v134
	v_exp_f32_e32 v141, v141
	s_nop 0
	v_add_f32_e32 v141, 1.0, v141
	v_div_scale_f32 v142, s[10:11], v141, v141, v134
	v_rcp_f32_e32 v143, v142
	v_div_scale_f32 v144, vcc, v134, v141, v134
	v_fma_f32 v145, -v142, v143, 1.0
	v_fmac_f32_e32 v143, v145, v143
	v_mul_f32_e32 v145, v144, v143
	v_fma_f32 v146, -v142, v145, v144
	v_fmac_f32_e32 v145, v146, v143
	v_fma_f32 v142, -v142, v145, v144
	v_div_fmas_f32 v142, v142, v143, v145
	v_div_fixup_f32 v147, v142, v141, v134
	ds_write_b32 v140, v147 offset:20480
	s_waitcnt vmcnt(10)
	v_mul_f32_e32 v141, 0xbfb8aa3b, v135
	v_exp_f32_e32 v141, v141
	s_nop 0
	v_add_f32_e32 v141, 1.0, v141
	v_div_scale_f32 v142, s[10:11], v141, v141, v135
	v_rcp_f32_e32 v143, v142
	v_div_scale_f32 v144, vcc, v135, v141, v135
	v_fma_f32 v145, -v142, v143, 1.0
	v_fmac_f32_e32 v143, v145, v143
	v_mul_f32_e32 v145, v144, v143
	v_fma_f32 v146, -v142, v145, v144
	v_fmac_f32_e32 v145, v146, v143
	v_fma_f32 v142, -v142, v145, v144
	v_div_fmas_f32 v142, v142, v143, v145
	v_div_fixup_f32 v147, v142, v141, v135
	ds_write_b32 v140, v147 offset:22528
	s_waitcnt vmcnt(9)
	v_mul_f32_e32 v141, 0xbfb8aa3b, v136
	v_exp_f32_e32 v141, v141
	s_nop 0
	v_add_f32_e32 v141, 1.0, v141
	v_div_scale_f32 v142, s[10:11], v141, v141, v136
	v_rcp_f32_e32 v143, v142
	v_div_scale_f32 v144, vcc, v136, v141, v136
	v_fma_f32 v145, -v142, v143, 1.0
	v_fmac_f32_e32 v143, v145, v143
	v_mul_f32_e32 v145, v144, v143
	v_fma_f32 v146, -v142, v145, v144
	v_fmac_f32_e32 v145, v146, v143
	v_fma_f32 v142, -v142, v145, v144
	v_div_fmas_f32 v142, v142, v143, v145
	v_div_fixup_f32 v147, v142, v141, v136
	ds_write_b32 v140, v147 offset:24576
	s_waitcnt vmcnt(8)
	v_mul_f32_e32 v141, 0xbfb8aa3b, v137
	v_exp_f32_e32 v141, v141
	s_nop 0
	v_add_f32_e32 v141, 1.0, v141
	v_div_scale_f32 v142, s[10:11], v141, v141, v137
	v_rcp_f32_e32 v143, v142
	v_div_scale_f32 v144, vcc, v137, v141, v137
	v_fma_f32 v145, -v142, v143, 1.0
	v_fmac_f32_e32 v143, v145, v143
	v_mul_f32_e32 v145, v144, v143
	v_fma_f32 v146, -v142, v145, v144
	v_fmac_f32_e32 v145, v146, v143
	v_fma_f32 v142, -v142, v145, v144
	v_div_fmas_f32 v142, v142, v143, v145
	v_div_fixup_f32 v147, v142, v141, v137
	ds_write_b32 v140, v147 offset:26624
	s_waitcnt vmcnt(7)
	v_mul_f32_e32 v141, 0xbfb8aa3b, v138
	v_exp_f32_e32 v141, v141
	s_nop 0
	v_add_f32_e32 v141, 1.0, v141
	v_div_scale_f32 v142, s[10:11], v141, v141, v138
	v_rcp_f32_e32 v143, v142
	v_div_scale_f32 v144, vcc, v138, v141, v138
	v_fma_f32 v145, -v142, v143, 1.0
	v_fmac_f32_e32 v143, v145, v143
	v_mul_f32_e32 v145, v144, v143
	v_fma_f32 v146, -v142, v145, v144
	v_fmac_f32_e32 v145, v146, v143
	v_fma_f32 v142, -v142, v145, v144
	v_div_fmas_f32 v142, v142, v143, v145
	v_div_fixup_f32 v147, v142, v141, v138
	ds_write_b32 v140, v147 offset:28672
	s_waitcnt vmcnt(6)
	v_mul_f32_e32 v141, 0xbfb8aa3b, v139
	v_exp_f32_e32 v141, v141
	s_nop 0
	v_add_f32_e32 v141, 1.0, v141
	v_div_scale_f32 v142, s[10:11], v141, v141, v139
	v_rcp_f32_e32 v143, v142
	v_div_scale_f32 v144, vcc, v139, v141, v139
	v_fma_f32 v145, -v142, v143, 1.0
	v_fmac_f32_e32 v143, v145, v143
	v_mul_f32_e32 v145, v144, v143
	v_fma_f32 v146, -v142, v145, v144
	v_fmac_f32_e32 v145, v146, v143
	v_fma_f32 v142, -v142, v145, v144
	v_div_fmas_f32 v142, v142, v143, v145
	v_div_fixup_f32 v147, v142, v141, v139
	ds_write_b32 v140, v147 offset:30720
.LBB0_22:
	s_or_b64 exec, exec, s[4:5]
	s_add_u32 s44, s54, 0x100000
	s_addc_u32 s45, s55, 0
	s_cmpk_gt_i32 s2, 0x2ff
	s_waitcnt lgkmcnt(0)
	s_barrier
	s_cbranch_scc1 .LBB0_29
	s_movk_i32 s0, 0x100
	v_and_b32_e32 v2, 63, v0
	v_lshlrev_b32_e32 v1, 2, v0
	v_cmp_gt_i32_e32 vcc, s0, v0
	v_lshlrev_b32_e32 v4, 2, v2
	s_movk_i32 s0, 0xff00
	v_and_b32_e32 v8, 60, v1
	v_and_b32_e32 v9, -16, v0
	v_ashrrev_i32_e32 v10, 6, v0
	v_lshlrev_b32_e32 v0, 6, v0
	v_and_or_b32 v1, v1, s0, v4
	v_lshl_add_u32 v3, v8, 2, 0
	v_and_b32_e32 v0, 0xfffffc00, v0
	v_add_u32_e32 v1, 0, v1
	v_mov_b32_e32 v5, 0
	v_add_u32_e32 v11, 0x8000, v1
	s_mov_b32 s3, 0xc000
	v_add_u32_e32 v12, v3, v0
	v_lshlrev_b32_e32 v4, 2, v2
	s_mov_b32 s8, s2
	s_mul_hi_i32 s0, s8, 0x2aaaaaab
	s_lshr_b32 s1, s0, 31
	s_ashr_i32 s5, s0, 5
	s_add_i32 s5, s5, s1
	s_mul_i32 s0, s5, 0xc0
	s_sub_i32 s0, s8, s0
	s_lshl_b32 s4, s0, 6
	s_branch .Lada_part_b

.Lada_part_b:
	v_or_b32_e32 v0, 6, v13
	v_lshl_add_u32 v89, v13, 2, 0
	v_mad_i64_i32 v[0:1], s[0:1], v0, s3, v[6:7]
	ds_read_b128 v[38:41], v89
	ds_read_b128 v[42:45], v89 offset:16
	global_load_dwordx4 v[46:49], v[0:1], off nt
	v_or_b32_e32 v2, 7, v13
	v_or_b32_e32 v3, 8, v13
	v_or_b32_e32 v74, 9, v13
	ds_read_b128 v[50:53], v89 offset:8192
	ds_read_b128 v[54:57], v89 offset:8208
	ds_read_b128 v[58:61], v89 offset:16384
	ds_read_b128 v[62:65], v89 offset:16400
	ds_read_b128 v[66:69], v89 offset:24576
	ds_read_b128 v[70:73], v89 offset:24592
	v_mad_i64_i32 v[82:83], s[0:1], v2, s3, v[6:7]
	v_mad_i64_i32 v[84:85], s[0:1], v3, s3, v[6:7]
	v_mad_i64_i32 v[86:87], s[0:1], v74, s3, v[6:7]
	global_load_dwordx4 v[74:77], v[82:83], off nt
	global_load_dwordx4 v[78:81], v[84:85], off nt
	global_load_dwordx4 v[0:3], v[86:87], off nt
	s_waitcnt lgkmcnt(7)
	v_mov_b32_e32 v88, v41
	s_waitcnt lgkmcnt(5)
	v_mov_b32_e32 v90, v53
	s_waitcnt lgkmcnt(3)
	v_mov_b32_e32 v92, v61
	s_waitcnt lgkmcnt(1)
	v_mov_b32_e32 v94, v69
	s_waitcnt vmcnt(9)
	v_pk_fma_f32 v[82:83], v[16:17], v[38:39], 0 op_sel_hi:[1,0,0]
	v_pk_fma_f32 v[84:85], v[14:15], v[38:39], 0 op_sel_hi:[1,0,0]
	v_pk_fma_f32 v[86:87], v[16:17], v[50:51], 0 op_sel_hi:[1,0,0]
	v_pk_fma_f32 v[96:97], v[14:15], v[50:51], 0 op_sel_hi:[1,0,0]
	v_pk_fma_f32 v[98:99], v[16:17], v[58:59], 0 op_sel_hi:[1,0,0]
	v_pk_fma_f32 v[100:101], v[14:15], v[58:59], 0 op_sel_hi:[1,0,0]
	v_pk_fma_f32 v[14:15], v[14:15], v[66:67], 0 op_sel_hi:[1,0,0]
	v_pk_fma_f32 v[16:17], v[16:17], v[66:67], 0 op_sel_hi:[1,0,0]
	s_waitcnt vmcnt(8)
	v_pk_fma_f32 v[82:83], v[20:21], v[38:39], v[82:83] op_sel:[0,1,0]
	v_pk_fma_f32 v[38:39], v[18:19], v[38:39], v[84:85] op_sel:[0,1,0]
	v_pk_fma_f32 v[84:85], v[20:21], v[50:51], v[86:87] op_sel:[0,1,0]
	v_pk_fma_f32 v[50:51], v[18:19], v[50:51], v[96:97] op_sel:[0,1,0]
	v_pk_fma_f32 v[86:87], v[20:21], v[58:59], v[98:99] op_sel:[0,1,0]
	v_pk_fma_f32 v[58:59], v[18:19], v[58:59], v[100:101] op_sel:[0,1,0]
	v_pk_fma_f32 v[14:15], v[18:19], v[66:67], v[14:15] op_sel:[0,1,0]
	v_pk_fma_f32 v[16:17], v[20:21], v[66:67], v[16:17] op_sel:[0,1,0]
	s_waitcnt vmcnt(7)
	v_pk_fma_f32 v[18:19], v[24:25], v[40:41], v[82:83] op_sel_hi:[1,0,1]
	v_pk_fma_f32 v[20:21], v[22:23], v[40:41], v[38:39] op_sel_hi:[1,0,1]
	v_pk_fma_f32 v[38:39], v[24:25], v[52:53], v[84:85] op_sel_hi:[1,0,1]
	v_pk_fma_f32 v[40:41], v[22:23], v[52:53], v[50:51] op_sel_hi:[1,0,1]
	v_pk_fma_f32 v[52:53], v[22:23], v[60:61], v[58:59] op_sel_hi:[1,0,1]
	v_pk_fma_f32 v[14:15], v[22:23], v[68:69], v[14:15] op_sel_hi:[1,0,1]
	v_pk_fma_f32 v[50:51], v[24:25], v[60:61], v[86:87] op_sel_hi:[1,0,1]
	v_pk_fma_f32 v[16:17], v[24:25], v[68:69], v[16:17] op_sel_hi:[1,0,1]
	s_waitcnt vmcnt(6)
	v_pk_fma_f32 v[18:19], v[28:29], v[88:89], v[18:19] op_sel_hi:[1,0,1]
	v_pk_fma_f32 v[20:21], v[26:27], v[88:89], v[20:21] op_sel_hi:[1,0,1]
	v_pk_fma_f32 v[22:23], v[28:29], v[90:91], v[38:39] op_sel_hi:[1,0,1]
	v_pk_fma_f32 v[24:25], v[26:27], v[90:91], v[40:41] op_sel_hi:[1,0,1]
	v_pk_fma_f32 v[40:41], v[26:27], v[92:93], v[52:53] op_sel_hi:[1,0,1]
	v_pk_fma_f32 v[26:27], v[26:27], v[94:95], v[14:15] op_sel_hi:[1,0,1]
	v_or_b32_e32 v14, 10, v13
	v_pk_fma_f32 v[38:39], v[28:29], v[92:93], v[50:51] op_sel_hi:[1,0,1]
	v_pk_fma_f32 v[28:29], v[28:29], v[94:95], v[16:17] op_sel_hi:[1,0,1]
	s_waitcnt vmcnt(5)
	v_pk_fma_f32 v[50:51], v[32:33], v[42:43], v[18:19] op_sel_hi:[1,0,1]
	v_mad_i64_i32 v[14:15], s[0:1], v14, s3, v[6:7]
	v_pk_fma_f32 v[52:53], v[30:31], v[42:43], v[20:21] op_sel_hi:[1,0,1]
	v_pk_fma_f32 v[22:23], v[32:33], v[54:55], v[22:23] op_sel_hi:[1,0,1]
	v_or_b32_e32 v18, 11, v13
	global_load_dwordx4 v[14:17], v[14:15], off nt
	v_pk_fma_f32 v[24:25], v[30:31], v[54:55], v[24:25] op_sel_hi:[1,0,1]
	v_pk_fma_f32 v[38:39], v[32:33], v[62:63], v[38:39] op_sel_hi:[1,0,1]
	v_pk_fma_f32 v[40:41], v[30:31], v[62:63], v[40:41] op_sel_hi:[1,0,1]
	v_mad_i64_i32 v[18:19], s[0:1], v18, s3, v[6:7]
	s_waitcnt lgkmcnt(0)
	v_pk_fma_f32 v[28:29], v[32:33], v[70:71], v[28:29] op_sel_hi:[1,0,1]
	v_pk_fma_f32 v[26:27], v[30:31], v[70:71], v[26:27] op_sel_hi:[1,0,1]
	s_waitcnt vmcnt(5)
	v_pk_fma_f32 v[30:31], v[36:37], v[42:43], v[50:51] op_sel:[0,1,0]
	v_pk_fma_f32 v[32:33], v[34:35], v[42:43], v[52:53] op_sel:[0,1,0]
	v_pk_fma_f32 v[42:43], v[36:37], v[54:55], v[22:23] op_sel:[0,1,0]
	v_or_b32_e32 v22, 12, v13
	global_load_dwordx4 v[18:21], v[18:19], off nt
	v_pk_fma_f32 v[50:51], v[34:35], v[54:55], v[24:25] op_sel:[0,1,0]
	v_mad_i64_i32 v[22:23], s[0:1], v22, s3, v[6:7]
	v_pk_fma_f32 v[40:41], v[34:35], v[62:63], v[40:41] op_sel:[0,1,0]
	v_pk_fma_f32 v[34:35], v[34:35], v[70:71], v[26:27] op_sel:[0,1,0]
	v_or_b32_e32 v26, 13, v13
	global_load_dwordx4 v[22:25], v[22:23], off nt
	s_waitcnt vmcnt(6)
	v_pk_fma_f32 v[52:53], v[48:49], v[44:45], v[30:31] op_sel_hi:[1,0,1]
	v_mad_i64_i32 v[26:27], s[0:1], v26, s3, v[6:7]
	v_or_b32_e32 v30, 14, v13
	v_pk_fma_f32 v[38:39], v[36:37], v[62:63], v[38:39] op_sel:[0,1,0]
	v_pk_fma_f32 v[36:37], v[36:37], v[70:71], v[28:29] op_sel:[0,1,0]
	global_load_dwordx4 v[26:29], v[26:27], off nt
	v_mad_i64_i32 v[30:31], s[0:1], v30, s3, v[6:7]
	v_or_b32_e32 v13, 15, v13
	v_pk_fma_f32 v[54:55], v[46:47], v[44:45], v[32:33] op_sel_hi:[1,0,1]
	global_load_dwordx4 v[30:33], v[30:31], off nt
	v_mad_i64_i32 v[6:7], s[0:1], v13, s3, v[6:7]
	v_pk_fma_f32 v[42:43], v[48:49], v[56:57], v[42:43] op_sel_hi:[1,0,1]
	v_pk_fma_f32 v[50:51], v[46:47], v[56:57], v[50:51] op_sel_hi:[1,0,1]
	v_pk_fma_f32 v[58:59], v[48:49], v[64:65], v[38:39] op_sel_hi:[1,0,1]
	v_pk_fma_f32 v[60:61], v[46:47], v[64:65], v[40:41] op_sel_hi:[1,0,1]
	v_pk_fma_f32 v[62:63], v[48:49], v[72:73], v[36:37] op_sel_hi:[1,0,1]
	v_pk_fma_f32 v[66:67], v[46:47], v[72:73], v[34:35] op_sel_hi:[1,0,1]
	ds_read_b128 v[34:37], v89 offset:32
	ds_read_b128 v[38:41], v89 offset:48
	global_load_dwordx4 v[46:49], v[6:7], off nt
	v_mov_b32_e32 v44, v57
	s_waitcnt vmcnt(8)
	v_pk_fma_f32 v[68:69], v[76:77], v[44:45], v[42:43] op_sel_hi:[1,0,1]
	v_mov_b32_e32 v42, v65
	v_mov_b32_e32 v6, v45
	v_pk_fma_f32 v[82:83], v[76:77], v[42:43], v[58:59] op_sel_hi:[1,0,1]
	v_pk_fma_f32 v[84:85], v[74:75], v[42:43], v[60:61] op_sel_hi:[1,0,1]
	v_mov_b32_e32 v42, v73
	v_pk_fma_f32 v[52:53], v[76:77], v[6:7], v[52:53] op_sel_hi:[1,0,1]
	v_pk_fma_f32 v[6:7], v[74:75], v[6:7], v[54:55] op_sel_hi:[1,0,1]
	v_pk_fma_f32 v[70:71], v[74:75], v[44:45], v[50:51] op_sel_hi:[1,0,1]
	v_pk_fma_f32 v[72:73], v[76:77], v[42:43], v[62:63] op_sel_hi:[1,0,1]
	v_pk_fma_f32 v[74:75], v[74:75], v[42:43], v[66:67] op_sel_hi:[1,0,1]
	ds_read_b128 v[42:45], v89 offset:8224
	s_waitcnt vmcnt(7) lgkmcnt(2)
	v_pk_fma_f32 v[76:77], v[80:81], v[34:35], v[52:53] op_sel_hi:[1,0,1]
	ds_read_b128 v[50:53], v89 offset:16416
	ds_read_b128 v[54:57], v89 offset:8240
	ds_read_b128 v[58:61], v89 offset:24608
	ds_read_b128 v[62:65], v89 offset:16432
	v_pk_fma_f32 v[6:7], v[78:79], v[34:35], v[6:7] op_sel_hi:[1,0,1]
	s_waitcnt lgkmcnt(4)
	v_pk_fma_f32 v[86:87], v[80:81], v[42:43], v[68:69] op_sel_hi:[1,0,1]
	ds_read_b128 v[66:69], v89 offset:24624
	v_pk_fma_f32 v[70:71], v[78:79], v[42:43], v[70:71] op_sel_hi:[1,0,1]
	s_waitcnt lgkmcnt(4)
	v_pk_fma_f32 v[82:83], v[80:81], v[50:51], v[82:83] op_sel_hi:[1,0,1]
	v_pk_fma_f32 v[84:85], v[78:79], v[50:51], v[84:85] op_sel_hi:[1,0,1]
	s_waitcnt lgkmcnt(2)
	v_pk_fma_f32 v[74:75], v[78:79], v[58:59], v[74:75] op_sel_hi:[1,0,1]
	v_pk_fma_f32 v[72:73], v[80:81], v[58:59], v[72:73] op_sel_hi:[1,0,1]
	s_waitcnt vmcnt(6)
	v_pk_fma_f32 v[76:77], v[2:3], v[34:35], v[76:77] op_sel:[0,1,0]
	v_pk_fma_f32 v[6:7], v[0:1], v[34:35], v[6:7] op_sel:[0,1,0]
	v_pk_fma_f32 v[34:35], v[2:3], v[42:43], v[86:87] op_sel:[0,1,0]
	v_pk_fma_f32 v[42:43], v[0:1], v[42:43], v[70:71] op_sel:[0,1,0]
	v_pk_fma_f32 v[70:71], v[2:3], v[50:51], v[82:83] op_sel:[0,1,0]
	v_pk_fma_f32 v[50:51], v[0:1], v[50:51], v[84:85] op_sel:[0,1,0]
	v_pk_fma_f32 v[0:1], v[0:1], v[58:59], v[74:75] op_sel:[0,1,0]
	v_pk_fma_f32 v[2:3], v[2:3], v[58:59], v[72:73] op_sel:[0,1,0]
	s_waitcnt vmcnt(5)
	v_pk_fma_f32 v[58:59], v[16:17], v[36:37], v[76:77] op_sel_hi:[1,0,1]
	v_pk_fma_f32 v[6:7], v[14:15], v[36:37], v[6:7] op_sel_hi:[1,0,1]
	v_pk_fma_f32 v[34:35], v[16:17], v[44:45], v[34:35] op_sel_hi:[1,0,1]
	v_pk_fma_f32 v[42:43], v[14:15], v[44:45], v[42:43] op_sel_hi:[1,0,1]
	v_pk_fma_f32 v[50:51], v[14:15], v[52:53], v[50:51] op_sel_hi:[1,0,1]
	v_pk_fma_f32 v[0:1], v[14:15], v[60:61], v[0:1] op_sel_hi:[1,0,1]
	v_mov_b32_e32 v14, v37
	v_mov_b32_e32 v44, v61
	v_pk_fma_f32 v[70:71], v[16:17], v[52:53], v[70:71] op_sel_hi:[1,0,1]
	v_pk_fma_f32 v[2:3], v[16:17], v[60:61], v[2:3] op_sel_hi:[1,0,1]
	v_mov_b32_e32 v36, v53
	s_waitcnt vmcnt(4)
	v_pk_fma_f32 v[16:17], v[20:21], v[14:15], v[58:59] op_sel_hi:[1,0,1]
	v_pk_fma_f32 v[6:7], v[18:19], v[14:15], v[6:7] op_sel_hi:[1,0,1]
	v_mov_b32_e32 v14, v45
	v_pk_fma_f32 v[0:1], v[18:19], v[44:45], v[0:1] op_sel_hi:[1,0,1]
	v_pk_fma_f32 v[34:35], v[20:21], v[14:15], v[34:35] op_sel_hi:[1,0,1]
	v_pk_fma_f32 v[14:15], v[18:19], v[14:15], v[42:43] op_sel_hi:[1,0,1]
	v_pk_fma_f32 v[42:43], v[20:21], v[36:37], v[70:71] op_sel_hi:[1,0,1]
	v_pk_fma_f32 v[36:37], v[18:19], v[36:37], v[50:51] op_sel_hi:[1,0,1]
	v_pk_fma_f32 v[2:3], v[20:21], v[44:45], v[2:3] op_sel_hi:[1,0,1]
	s_waitcnt vmcnt(3)
	v_pk_fma_f32 v[16:17], v[24:25], v[38:39], v[16:17] op_sel_hi:[1,0,1]
	v_pk_fma_f32 v[6:7], v[22:23], v[38:39], v[6:7] op_sel_hi:[1,0,1]
	s_waitcnt lgkmcnt(0)
	v_pk_fma_f32 v[0:1], v[22:23], v[66:67], v[0:1] op_sel_hi:[1,0,1]
	v_pk_fma_f32 v[18:19], v[24:25], v[54:55], v[34:35] op_sel_hi:[1,0,1]
	v_pk_fma_f32 v[14:15], v[22:23], v[54:55], v[14:15] op_sel_hi:[1,0,1]
	v_pk_fma_f32 v[34:35], v[22:23], v[62:63], v[36:37] op_sel_hi:[1,0,1]
	v_pk_fma_f32 v[2:3], v[24:25], v[66:67], v[2:3] op_sel_hi:[1,0,1]
	s_waitcnt vmcnt(2)
	v_pk_fma_f32 v[16:17], v[28:29], v[38:39], v[16:17] op_sel:[0,1,0]
	v_pk_fma_f32 v[6:7], v[26:27], v[38:39], v[6:7] op_sel:[0,1,0]
	v_pk_fma_f32 v[0:1], v[26:27], v[66:67], v[0:1] op_sel:[0,1,0]
	v_pk_fma_f32 v[20:21], v[24:25], v[62:63], v[42:43] op_sel_hi:[1,0,1]
	v_pk_fma_f32 v[18:19], v[28:29], v[54:55], v[18:19] op_sel:[0,1,0]
	v_pk_fma_f32 v[14:15], v[26:27], v[54:55], v[14:15] op_sel:[0,1,0]
	v_pk_fma_f32 v[22:23], v[26:27], v[62:63], v[34:35] op_sel:[0,1,0]
	v_pk_fma_f32 v[2:3], v[28:29], v[66:67], v[2:3] op_sel:[0,1,0]
	s_waitcnt vmcnt(1)
	v_pk_fma_f32 v[16:17], v[32:33], v[40:41], v[16:17] op_sel_hi:[1,0,1]
	v_pk_fma_f32 v[6:7], v[30:31], v[40:41], v[6:7] op_sel_hi:[1,0,1]
	v_pk_fma_f32 v[26:27], v[30:31], v[68:69], v[0:1] op_sel_hi:[1,0,1]
	v_mov_b32_e32 v0, v41
	v_pk_fma_f32 v[20:21], v[28:29], v[62:63], v[20:21] op_sel:[0,1,0]
	v_pk_fma_f32 v[18:19], v[32:33], v[56:57], v[18:19] op_sel_hi:[1,0,1]
	v_pk_fma_f32 v[14:15], v[30:31], v[56:57], v[14:15] op_sel_hi:[1,0,1]
	v_pk_fma_f32 v[24:25], v[32:33], v[68:69], v[2:3] op_sel_hi:[1,0,1]
	s_waitcnt vmcnt(0)
	v_pk_fma_f32 v[2:3], v[48:49], v[0:1], v[16:17] op_sel_hi:[1,0,1]
	v_pk_fma_f32 v[0:1], v[46:47], v[0:1], v[6:7] op_sel_hi:[1,0,1]
	v_mov_b32_e32 v6, v57
	v_pk_fma_f32 v[20:21], v[32:33], v[64:65], v[20:21] op_sel_hi:[1,0,1]
	v_pk_fma_f32 v[22:23], v[30:31], v[64:65], v[22:23] op_sel_hi:[1,0,1]
	v_pk_fma_f32 v[16:17], v[48:49], v[6:7], v[18:19] op_sel_hi:[1,0,1]
	v_pk_fma_f32 v[14:15], v[46:47], v[6:7], v[14:15] op_sel_hi:[1,0,1]
	v_mov_b32_e32 v6, v65
	v_pk_fma_f32 v[20:21], v[48:49], v[6:7], v[20:21] op_sel_hi:[1,0,1]
	v_pk_fma_f32 v[18:19], v[46:47], v[6:7], v[22:23] op_sel_hi:[1,0,1]
	v_mov_b32_e32 v6, v69
	v_pk_fma_f32 v[24:25], v[48:49], v[6:7], v[24:25] op_sel_hi:[1,0,1]
	v_pk_fma_f32 v[22:23], v[46:47], v[6:7], v[26:27] op_sel_hi:[1,0,1]
	ds_write_b128 v12, v[0:3] offset:32768
	ds_write_b128 v12, v[14:17] offset:33024
	ds_write_b128 v12, v[18:21] offset:33280
	ds_write_b128 v12, v[22:25] offset:33536
	s_waitcnt lgkmcnt(0)
	s_barrier
	s_and_saveexec_b64 s[6:7], vcc
	s_cbranch_execz .LBB0_24
	v_mov_b32_e32 v0, 0
	s_mov_b32 s0, 0
